# static s_setprio 1 for waves 4-7 also in mixer phases 1 and 3 (reset at each phase exit)
# speedup vs baseline: 1.0062x; 1.0016x over previous
; #define GAS __attribute__((address_space(1)))
; #define LAS __attribute__((address_space(3)))
; #define LDS_WAIT() asm volatile("s_waitcnt lgkmcnt(0)" ::: "memory")
; __device__ __forceinline__ int xb_lane() { int z = 0; asm volatile("" : "+v"(z)); return (int)__builtin_amdgcn_mbcnt_hi(~0u, __builtin_amdgcn_mbcnt_lo(~0u, (unsigned)z)); }
; __device__ __forceinline__ void mixer_phase1(Frame& FF, int l) {
;     Frame F = FF; F.lane = xb_lane(); F.tid = F.wave * 64 + F.lane;
;     const bf16* P = (const bf16*)(F.ws + WS_P);
;     const ScanBufs<128> A = bufsA(F.ws); const ScanBufs<64> B = bufsB(F.ws);
;     const float* LB = (const float*)(F.ws + WS_TAB + TAB_LB) + (size_t)l * 2048;
;     const f32x2* RR = (const f32x2*)(F.ws + WS_TAB + TAB_RR); const f32x2* RC = (const f32x2*)(F.ws + WS_TAB + TAB_RC);
;     const int gw = F.vcu * NWAVES + F.wave, NGW = F.G * NWAVES;
;     LAS v4u* Wl = (LAS v4u*)(F.lds + F.wave * 8192);
;     LAS f32x2* RCl = (LAS f32x2*)(F.lds + 65536);
;     { const v4u v = *(const GAS v4u*)((const char*)RC + F.tid * 16); *(LAS v4u*)((LAS unsigned char*)RCl + F.tid * 16) = v; }
;     LDS_WAIT(); __syncthreads();
;     LAS v4u* Gl = (LAS v4u*)(F.lds + 73728 + F.wave * 2048);
;     constexpr int U_F = NCH * 4, U_K = NCH * 4, U_V = NCH * 4, U_QA = 0, U_QB = 0, U_ALL = U_F + U_K + U_V + U_QA + U_QB;
;     int u0 = -1;
;     const bool deal = (F.G == 256); if (deal) { const int w = F.wave, cu = F.vcu;
;         if (w < 4) u0 = w * 256 + cu;
;         else if (w == 4 && cu < 128) u0 = 1024 + cu;
;         else { const int li = cu < 128 ? cu * 3 + (w - 5) : 384 + (cu - 128) * 4 + (w - 4); if (U_F + U_K + li < U_ALL) u0 = U_F + U_K + li; }
;     }
;     const int ustep = deal ? 1 : NGW; const int uend = deal ? 1 : U_ALL;
.LBB0_402:
	v_readlane_b32 s0, v248, 0
	v_readlane_b32 s1, v248, 1
	s_mov_b64 s[4:5], s[0:1]
	s_cmp_le_i32 s4, s16
	v_readlane_b32 s2, v248, 2
	v_readlane_b32 s3, v248, 3
	s_cselect_b64 s[0:1], -1, 0
	s_cmp_lt_i32 s16, s5
	s_cselect_b64 s[2:3], -1, 0
	s_and_b64 s[2:3], s[0:1], s[2:3]
	s_mov_b64 s[0:1], -1
	s_and_b64 vcc, exec, s[2:3]
	s_cbranch_vccnz .LBB0_404
	v_readlane_b32 s0, v245, 49
	s_add_i32 s16, s0, 5
	s_mov_b64 s[0:1], 0
.LBB0_404:
	s_andn2_b64 vcc, exec, s[0:1]
	s_cbranch_vccnz .LBB0_902
	v_readlane_b32 s100, v251, 40
	s_nop 0
	s_bitcmp1_b32 s100, 10
	s_cbranch_scc0 .Lprio_m1_skip
	s_setprio 1
.Lprio_m1_skip:
	v_mov_b32_e32 v0, v65
	v_readlane_b32 s0, v249, 59
	v_mbcnt_lo_u32_b32 v0, -1, v0
	v_mbcnt_hi_u32_b32 v0, -1, v0
	v_lshl_add_u32 v4, v0, 4, s0
	v_readlane_b32 s0, v249, 53
	v_ashrrev_i32_e32 v5, 31, v4
	v_readlane_b32 s1, v249, 54
	s_mov_b32 s14, -1
	s_movk_i32 s15, 0x6c0
	v_lshl_add_u64 v[0:1], s[0:1], 0, v[4:5]
	global_load_dwordx4 v[0:3], v[0:1], off
	v_add_u32_e32 v4, 0, v4
	v_readlane_b32 s0, v248, 16
	v_add_u32_e32 v4, 0x10000, v4
	v_readlane_b32 s1, v248, 17
	s_andn2_b64 vcc, exec, s[0:1]
	v_readlane_b32 s0, v245, 22
	v_readlane_b32 s1, v245, 23
	s_mov_b32 s16, s0
	v_readlane_b32 s0, v245, 26
	s_mov_b32 s17, s0
	v_readlane_b32 s1, v245, 27
	s_waitcnt vmcnt(0)
	ds_write_b128 v4, v[0:3]
	s_waitcnt lgkmcnt(0)
	s_waitcnt lgkmcnt(0)
	s_barrier
	s_cbranch_vccnz .LBB0_407
	s_mov_b32 s15, 1
	s_mov_b32 s16, 0
	s_mov_b32 s17, 1
	v_readlane_b32 s14, v246, 50

; #define RUN(kind, ...) do { _Pragma("nounroll") for (int rep_ = 0; rep_ < ((REP_KIND == (kind)) ? 2 : 1); ++rep_) { __VA_ARGS__; } } while (0)
; #define SEAM(k) do { if (IN((k) + 1)) { if (use_bar) { xcd_barrier(bar); if (REP_KIND == 9) xcd_barrier(bar); } else if (F.tid == 0) __hip_atomic_store(F.ctl + CW_TMO, 0xBADBA0u, RLX_AGENT); } } while (0)
; __global__ void __launch_bounds__(NWAVES * 64, 2) fwd_kernel(Args args) {
;     ...
;         if (IN(pb + 1)) { RUN(2, mixer_phase1(F, l)); SEAM(pb + 1); }
;         if (IN(pb + 2)) { mixer_phase2(F, l, 0); if (REP_KIND == 3) mixer_phase2(F, l, 1); SEAM(pb + 2); }
.LBB0_902:
	s_setprio 0
	v_readlane_b32 s0, v248, 0
	v_readlane_b32 s1, v248, 1
	s_mov_b64 s[4:5], s[0:1]
	s_cmp_le_i32 s4, s16
	v_readlane_b32 s2, v248, 2
	v_readlane_b32 s3, v248, 3
	s_cselect_b64 s[0:1], -1, 0
	s_cmp_lt_i32 s16, s5
	s_cselect_b64 s[2:3], -1, 0
	s_and_b64 s[2:3], s[0:1], s[2:3]
	s_mov_b64 s[0:1], -1
	s_and_b64 vcc, exec, s[2:3]
	s_cbranch_vccnz .LBB0_904
	v_readlane_b32 s0, v245, 49
	s_add_i32 s16, s0, 6
	s_mov_b64 s[0:1], 0

; #define LAS __attribute__((address_space(3)))
; __device__ __forceinline__ int xb_lane() { int z = 0; asm volatile("" : "+v"(z)); return (int)__builtin_amdgcn_mbcnt_hi(~0u, __builtin_amdgcn_mbcnt_lo(~0u, (unsigned)z)); }
; #define RUN(kind, ...) do { _Pragma("nounroll") for (int rep_ = 0; rep_ < ((REP_KIND == (kind)) ? 2 : 1); ++rep_) { __VA_ARGS__; } } while (0)
; #define SEAM(k) do { if (IN((k) + 1)) { if (use_bar) { xcd_barrier(bar); if (REP_KIND == 9) xcd_barrier(bar); } else if (F.tid == 0) __hip_atomic_store(F.ctl + CW_TMO, 0xBADBA0u, RLX_AGENT); } } while (0)
; __device__ __forceinline__ void mixer_phase3(Frame& FF, int l) {
;     Frame F = FF; F.lane = xb_lane(); F.tid = F.wave * 64 + F.lane; const int lane = F.lane;
;     const bf16* P = (const bf16*)(F.ws + WS_P); bf16* Y = (bf16*)(F.ws + WS_Y);
;     const ScanBufs<128> A = bufsA(F.ws); const ScanBufs<64> B = bufsB(F.ws);
;     const int nch = (l == DEPTH - 1) ? 128 : NCH;
;     const int nu = nch * 8;
;     LAS unsigned char* W = F.lds + F.wave * P3_WBYTES;
;     const int NGW = F.G * NWAVES; const int gw0 = F.wave * F.G + F.vcu; const int gw1 = (F.G == 256) ? ((F.wave == 5) ? NGW + F.vcu : 2 * nu) : gw0 + NGW;
;     for (int ui = 0; ui < 16; ++ui) { const int u = ui == 0 ? gw0 : (F.G == 256 ? (ui == 1 ? gw1 : 2 * nu) : gw0 + ui * NGW); if (u >= 2 * nu) break;
; __global__ void __launch_bounds__(NWAVES * 64, 2) fwd_kernel(Args args) {
;     ...
;         if (IN(pb + 2)) { mixer_phase2(F, l, 0); if (REP_KIND == 3) mixer_phase2(F, l, 1); SEAM(pb + 2); }
;         if (IN(pb + 3)) { RUN(4, mixer_phase3(F, l)); SEAM(pb + 3); }
.LBB0_1080:
	s_setprio 0
	v_readlane_b32 s0, v248, 0
	v_readlane_b32 s1, v248, 1
	s_mov_b64 s[4:5], s[0:1]
	s_cmp_le_i32 s4, s16
	v_readlane_b32 s2, v248, 2
	v_readlane_b32 s3, v248, 3
	s_cselect_b64 s[0:1], -1, 0
	s_cmp_lt_i32 s16, s5
	s_cselect_b64 s[2:3], -1, 0
	s_and_b64 s[2:3], s[0:1], s[2:3]
	s_mov_b64 s[0:1], -1
	s_and_b64 vcc, exec, s[2:3]
	s_cbranch_vccnz .LBB0_1082
	v_readlane_b32 s0, v245, 49
	s_add_i32 s16, s0, 7
	s_mov_b64 s[0:1], 0
.LBB0_1082:
	s_andn2_b64 vcc, exec, s[0:1]
	s_cbranch_vccnz .LBB0_1160
	v_readlane_b32 s100, v251, 40
	s_nop 0
	s_bitcmp1_b32 s100, 10
	s_cbranch_scc0 .Lprio_m3_skip
	s_setprio 1
.Lprio_m3_skip:
	v_readlane_b32 s0, v245, 50
	v_readlane_b32 s1, v245, 51
	s_and_b64 s[0:1], s[0:1], exec
	s_movk_i32 s0, 0x480
	s_cselect_b32 s0, 0x400, s0
	v_writelane_b32 v245, s0, 60
	s_lshl_b32 s33, s0, 1
	v_readlane_b32 s0, v245, 52
	v_readlane_b32 s1, v245, 53
	s_lshl_b32 s0, s0, 7
	s_mov_b32 s1, s77
	v_writelane_b32 v245, s0, 61
	v_mov_b32_e32 v0, v65
	v_writelane_b32 v244, s33, 0
	v_writelane_b32 v245, s1, 62
	s_mov_b32 s0, 0
	v_writelane_b32 v245, s0, 63
	s_branch .LBB0_1086

; #define RUN(kind, ...) do { _Pragma("nounroll") for (int rep_ = 0; rep_ < ((REP_KIND == (kind)) ? 2 : 1); ++rep_) { __VA_ARGS__; } } while (0)
; #define SEAM(k) do { if (IN((k) + 1)) { if (use_bar) { xcd_barrier(bar); if (REP_KIND == 9) xcd_barrier(bar); } else if (F.tid == 0) __hip_atomic_store(F.ctl + CW_TMO, 0xBADBA0u, RLX_AGENT); } } while (0)
; __global__ void __launch_bounds__(NWAVES * 64, 2) fwd_kernel(Args args) {
;     ...
;         if (IN(pb + 3)) { RUN(4, mixer_phase3(F, l)); SEAM(pb + 3); }
;         if (IN(pb + 4)) {
.LBB0_1160:
	s_setprio 0
	v_readlane_b32 s0, v248, 0
	v_readlane_b32 s1, v248, 1
	s_mov_b64 s[4:5], s[0:1]
	s_cmp_le_i32 s4, s16
	v_readlane_b32 s2, v248, 2
	v_readlane_b32 s3, v248, 3
	s_cselect_b64 s[0:1], -1, 0
	s_cmp_lt_i32 s16, s5
	s_cselect_b64 s[2:3], -1, 0
	s_and_b64 s[2:3], s[0:1], s[2:3]
	s_mov_b64 s[0:1], -1
	s_and_b64 vcc, exec, s[2:3]
	s_cbranch_vccnz .LBB0_1162
	v_readlane_b32 s0, v245, 49
	s_add_i32 s16, s0, 8
	s_mov_b64 s[0:1], 0
